# final candidate variant: phase-B items-first fraction mode 101 (100 = 1/4, 101 = 3/4 of WGs)
# baseline (speedup 1.0000x reference)
; __global__ void __launch_bounds__(256, 2) hybrid_megakernel(Params p) {
;     ...
;     xcd_barrier(xg);
;     for (int vb = bid; vb < 512; vb += nb) {
;       { const int q2 = vb >> 3; inproj_tile<4>(p, l, (vb & 7) * 16 + (q2 & 15), 8 + (q2 >> 4), lds); }
;       if (vb < 64) cmp_item(p, l, vb, lds);
;       else {
;         const int j = vb - 64;
;         if (vb >= 256) { const int i2 = (vb - 256) >> 3; inproj_tile<2>(p, l, (vb & 7) * 16 + (i2 & 15), 24 + (i2 >> 4), lds); }
;         win_item(p, j, lds);
;         if (j + 448 < 512) win_item(p, j + 448, lds);
;         for (int it = j; it < 1536; it += 448) dil_item(p, it, lds);
;       }
;     }
.LBB0_213:
	s_or_b64 exec, exec, s[0:1]
	v_readlane_b32 s0, v235, 23
	v_readlane_b32 s1, v235, 24
	s_andn2_b64 vcc, exec, s[0:1]
	s_waitcnt lgkmcnt(0)
	v_cndmask_b32_e64 v0, 0, 1, s[0:1]
	v_cmp_ne_u32_e64 s[2:3], 1, v0
	s_barrier
	s_nop 0
	v_writelane_b32 v234, s2, 27
	s_nop 1
	v_writelane_b32 v234, s3, 28
	s_cbranch_vccnz .LBB0_298
	v_readlane_b32 s0, v234, 24
	s_mul_i32 s28, s0, 0xd00
	s_lshl_b32 s29, s0, 1
	v_readlane_b32 s30, v234, 18
	v_readlane_b32 s31, v234, 17
	v_readlane_b32 s34, v234, 14
	v_readlane_b32 s35, v234, 13
	v_readlane_b32 s36, v235, 0
	s_nop 1
	s_bfe_u32 s98, s36, 0x20003
	s_cmp_eq_u32 s98, 0
	s_cselect_b32 s98, 0, 1
	s_branch .LBB0_217
